# diff attention K/V LDS-DMA issue block slimmed: SGPR base + 32-bit VGPR offset per piece, no m0 save/restore, no per-piece 64-bit VALU add; on top of v39
# speedup vs baseline: 1.0232x; 1.0021x over previous
; __device__ __forceinline__ void glds16(const void* gsrc, unsigned lds_dst) { unsigned keep;
;     asm volatile("s_mov_b32 %0, m0\n\ts_mov_b32 m0, %2\n\ts_nop 0\n\tglobal_load_lds_dwordx4 %1, off\n\ts_mov_b32 m0, %0" : "=&s"(keep) : "v"(gsrc), "s"(lds_dst) : "memory"); }
.Ldma_g0_0:
	s_andn2_b64 vcc, exec, s[4:5]
	s_cbranch_vccnz .LBB0_153
	s_lshl_b64 s[4:5], s[6:7], 6
	s_add_u32 s4, s4, s40
	s_addc_u32 s5, s5, s41
	s_mulk_i32 s5, 0x3000
	s_mul_hi_u32 s81, s4, 0x3000
	s_add_i32 s81, s81, s5
	s_mulk_i32 s4, 0x3000
	s_add_u32 s4, s22, s4
	s_addc_u32 s5, s23, s81
	s_lshl_b32 s81, s80, 16
	s_xor_b32 s82, s81, 0x10000
	v_lshlrev_b32_e32 v2, 1, v198
	v_lshlrev_b32_e32 v4, 1, v196
	s_add_i32 s83, s82, s50
	s_add_i32 s82, s82, s51
	s_add_u32 s96, s4, 0x30000
	s_addc_u32 s97, s5, 0
	s_add_u32 s98, s4, 0x60000
	s_addc_u32 s99, s5, 0
	s_add_u32 s100, s4, 0x90000
	s_addc_u32 s101, s5, 0
	s_mov_b32 m0, s83
	s_nop 0
	global_load_lds_dwordx4 v2, s[4:5]
	s_mov_b32 m0, s82
	s_nop 0
	global_load_lds_dwordx4 v4, s[4:5]
	s_add_i32 m0, s83, 0x2000
	s_nop 0
	global_load_lds_dwordx4 v2, s[96:97]
	s_add_i32 m0, s82, 0x2000
	s_nop 0
	global_load_lds_dwordx4 v4, s[96:97]
	s_add_i32 m0, s83, 0x4000
	s_nop 0
	global_load_lds_dwordx4 v2, s[98:99]
	s_add_i32 m0, s82, 0x4000
	s_nop 0
	global_load_lds_dwordx4 v4, s[98:99]
	s_add_i32 m0, s83, 0x6000
	s_nop 0
	global_load_lds_dwordx4 v2, s[100:101]
	s_add_i32 m0, s82, 0x6000
	s_nop 0
	global_load_lds_dwordx4 v4, s[100:101]

; __device__ __forceinline__ void glds16(const void* gsrc, unsigned lds_dst) { unsigned keep;
;     asm volatile("s_mov_b32 %0, m0\n\ts_mov_b32 m0, %2\n\ts_nop 0\n\tglobal_load_lds_dwordx4 %1, off\n\ts_mov_b32 m0, %0" : "=&s"(keep) : "v"(gsrc), "s"(lds_dst) : "memory"); }
.LBB0_193:
	s_cmp_eq_u32 s75, 1
	s_cbranch_scc0 .Ldma_skip_0
	s_andn2_b64 vcc, exec, s[94:95]
	s_cbranch_vccnz .Ldma_skip_0
	s_lshl_b64 s[4:5], s[6:7], 6
	s_add_u32 s4, s4, s40
	s_addc_u32 s5, s5, s41
	s_mulk_i32 s5, 0x3000
	s_mul_hi_u32 s81, s4, 0x3000
	s_add_i32 s81, s81, s5
	s_mulk_i32 s4, 0x3000
	s_add_u32 s4, s22, s4
	s_addc_u32 s5, s23, s81
	s_lshl_b32 s81, s80, 16
	s_xor_b32 s82, s81, 0x10000
	v_lshlrev_b32_e32 v2, 1, v198
	v_lshlrev_b32_e32 v4, 1, v196
	s_add_i32 s83, s82, s50
	s_add_i32 s82, s82, s51
	s_add_u32 s96, s4, 0x30000
	s_addc_u32 s97, s5, 0
	s_add_u32 s98, s4, 0x60000
	s_addc_u32 s99, s5, 0
	s_add_u32 s100, s4, 0x90000
	s_addc_u32 s101, s5, 0
	s_mov_b32 m0, s83
	s_nop 0
	global_load_lds_dwordx4 v2, s[4:5]
	s_mov_b32 m0, s82
	s_nop 0
	global_load_lds_dwordx4 v4, s[4:5]
	s_add_i32 m0, s83, 0x2000
	s_nop 0
	global_load_lds_dwordx4 v2, s[96:97]
	s_add_i32 m0, s82, 0x2000
	s_nop 0
	global_load_lds_dwordx4 v4, s[96:97]
	s_add_i32 m0, s83, 0x4000
	s_nop 0
	global_load_lds_dwordx4 v2, s[98:99]
	s_add_i32 m0, s82, 0x4000
	s_nop 0
	global_load_lds_dwordx4 v4, s[98:99]
	s_add_i32 m0, s83, 0x6000
	s_nop 0
	global_load_lds_dwordx4 v2, s[100:101]
	s_add_i32 m0, s82, 0x6000
	s_nop 0
	global_load_lds_dwordx4 v4, s[100:101]
